# K-loop: per-iteration pointer/cselect SALU preamble moved from phase 1 to end of phase 8 load segment (exit flag in vcc), pointer steps in M0 wait-state slots
# speedup vs baseline: 1.0017x; 1.0017x over previous
.LBB0_385:
	s_add_i32 s43, s6, -2
	s_add_u32 s0, s46, 0x80
	s_addc_u32 s1, s47, 0
	s_add_u32 s48, s44, 0x100
	v_mov_b32_e32 v2, 0
	s_addc_u32 s49, s45, 0
	s_mov_b32 s44, 0
	v_mov_b32_e32 v3, v2
	v_mov_b32_e32 v4, v2
	v_mov_b32_e32 v5, v2
	v_mov_b32_e32 v6, v2
	v_mov_b32_e32 v7, v2
	v_mov_b32_e32 v8, v2
	v_mov_b32_e32 v9, v2
	s_waitcnt vmcnt(0)
	v_mov_b32_e32 v18, v2
	v_mov_b32_e32 v19, v2
	v_mov_b32_e32 v20, v2
	v_mov_b32_e32 v21, v2
	v_mov_b32_e32 v22, v2
	v_mov_b32_e32 v23, v2
	v_mov_b32_e32 v24, v2
	v_mov_b32_e32 v25, v2
	v_mov_b32_e32 v34, v2
	v_mov_b32_e32 v35, v2
	v_mov_b32_e32 v36, v2
	v_mov_b32_e32 v37, v2
	v_mov_b32_e32 v38, v2
	v_mov_b32_e32 v39, v2
	v_mov_b32_e32 v40, v2
	v_mov_b32_e32 v41, v2
	v_mov_b32_e32 v50, v2
	v_mov_b32_e32 v51, v2
	v_mov_b32_e32 v52, v2
	v_mov_b32_e32 v53, v2
	v_mov_b32_e32 v54, v2
	v_mov_b32_e32 v55, v2
	v_mov_b32_e32 v56, v2
	v_mov_b32_e32 v57, v2
	v_mov_b32_e32 v10, v2
	v_mov_b32_e32 v11, v2
	v_mov_b32_e32 v12, v2
	v_mov_b32_e32 v13, v2
	v_mov_b32_e32 v14, v2
	v_mov_b32_e32 v15, v2
	v_mov_b32_e32 v16, v2
	v_mov_b32_e32 v17, v2
	v_mov_b32_e32 v26, v2
	v_mov_b32_e32 v27, v2
	v_mov_b32_e32 v28, v2
	v_mov_b32_e32 v29, v2
	v_mov_b32_e32 v30, v2
	v_mov_b32_e32 v31, v2
	v_mov_b32_e32 v32, v2
	v_mov_b32_e32 v33, v2
	v_mov_b32_e32 v42, v2
	v_mov_b32_e32 v43, v2
	v_mov_b32_e32 v44, v2
	v_mov_b32_e32 v45, v2
	v_mov_b32_e32 v46, v2
	v_mov_b32_e32 v47, v2
	v_mov_b32_e32 v48, v2
	v_mov_b32_e32 v49, v2
	v_mov_b32_e32 v58, v2
	v_mov_b32_e32 v59, v2
	v_mov_b32_e32 v60, v2
	v_mov_b32_e32 v61, v2
	v_mov_b32_e32 v62, v2
	v_mov_b32_e32 v63, v2
	v_mov_b32_e32 v64, v2
	v_mov_b32_e32 v65, v2
	v_mov_b32_e32 v66, v2
	v_mov_b32_e32 v67, v2
	v_mov_b32_e32 v68, v2
	v_mov_b32_e32 v69, v2
	v_mov_b32_e32 v70, v2
	v_mov_b32_e32 v71, v2
	v_mov_b32_e32 v72, v2
	v_mov_b32_e32 v73, v2
	v_mov_b32_e32 v82, v2
	v_mov_b32_e32 v83, v2
	s_waitcnt vmcnt(0)
	v_mov_b32_e32 v84, v2
	v_mov_b32_e32 v85, v2
	v_mov_b32_e32 v86, v2
	v_mov_b32_e32 v87, v2
	v_mov_b32_e32 v88, v2
	v_mov_b32_e32 v89, v2
	v_mov_b32_e32 v98, v2
	v_mov_b32_e32 v99, v2
	v_mov_b32_e32 v100, v2
	v_mov_b32_e32 v101, v2
	v_mov_b32_e32 v102, v2
	v_mov_b32_e32 v103, v2
	v_mov_b32_e32 v104, v2
	v_mov_b32_e32 v105, v2
	v_mov_b32_e32 v114, v2
	v_mov_b32_e32 v115, v2
	v_mov_b32_e32 v116, v2
	v_mov_b32_e32 v117, v2
	v_mov_b32_e32 v118, v2
	v_mov_b32_e32 v119, v2
	v_mov_b32_e32 v120, v2
	v_mov_b32_e32 v121, v2
	v_mov_b32_e32 v74, v2
	v_mov_b32_e32 v75, v2
	v_mov_b32_e32 v76, v2
	v_mov_b32_e32 v77, v2
	v_mov_b32_e32 v78, v2
	v_mov_b32_e32 v79, v2
	v_mov_b32_e32 v80, v2
	v_mov_b32_e32 v81, v2
	v_mov_b32_e32 v90, v2
	v_mov_b32_e32 v91, v2
	v_mov_b32_e32 v92, v2
	v_mov_b32_e32 v93, v2
	v_mov_b32_e32 v94, v2
	v_mov_b32_e32 v95, v2
	v_mov_b32_e32 v96, v2
	v_mov_b32_e32 v97, v2
	v_mov_b32_e32 v106, v2
	v_mov_b32_e32 v107, v2
	v_mov_b32_e32 v108, v2
	v_mov_b32_e32 v109, v2
	v_mov_b32_e32 v110, v2
	v_mov_b32_e32 v111, v2
	v_mov_b32_e32 v112, v2
	v_mov_b32_e32 v113, v2
	v_mov_b32_e32 v122, v2
	v_mov_b32_e32 v123, v2
	v_mov_b32_e32 v124, v2
	v_mov_b32_e32 v125, v2
	v_mov_b32_e32 v126, v2
	v_mov_b32_e32 v127, v2
	v_mov_b32_e32 v128, v2
	v_mov_b32_e32 v129, v2
	s_waitcnt lgkmcnt(0)
	s_add_i32 s71, s44, 2
	s_add_u32 s46, s0, 0x80
	s_addc_u32 s45, s1, 0
	s_cmp_eq_u32 s43, s44
	s_cselect_b32 s44, s72, s46
	s_cselect_b32 s45, s73, s45
	s_cselect_b32 s47, s75, s49
	s_cselect_b32 s46, s74, s48
	v_add_u32_e32 v0, 0x10000, v224
	ds_read_b128 v[130:133], v0
	ds_read_b128 v[134:137], v0 offset:1024
	ds_read_b128 v[138:141], v0 offset:2048
	ds_read_b128 v[142:145], v0 offset:3072
.LBB0_386:
	s_add_i32 m0, s98, 0xc000
	ds_read_b128 v[146:149], v229
	ds_read_b128 v[150:153], v229 offset:1024
	ds_read_b128 v[176:179], v229 offset:2048
	ds_read_b128 v[180:183], v229 offset:3072
	ds_read_b128 v[184:187], v229 offset:4096
	ds_read_b128 v[188:191], v229 offset:5120
	ds_read_b128 v[192:195], v229 offset:6144
	ds_read_b128 v[196:199], v229 offset:7168
	global_load_lds_dwordx4 v172, s[0:1]
	s_add_i32 m0, s98, 0xe000
	s_nop 0
	global_load_lds_dwordx4 v174, s[0:1]
	s_waitcnt lgkmcnt(8)
	s_barrier
	s_waitcnt lgkmcnt(0)
	v_mfma_f32_16x16x32_bf16 v[126:129], v[130:133], v[146:149], v[126:129]
	v_mfma_f32_16x16x32_bf16 v[122:125], v[138:141], v[146:149], v[122:125]
	v_mfma_f32_16x16x32_bf16 v[110:113], v[130:133], v[176:179], v[110:113]
	v_mfma_f32_16x16x32_bf16 v[106:109], v[138:141], v[176:179], v[106:109]
	v_mfma_f32_16x16x32_bf16 v[94:97], v[130:133], v[184:187], v[94:97]
	v_mfma_f32_16x16x32_bf16 v[90:93], v[138:141], v[184:187], v[90:93]
	v_mfma_f32_16x16x32_bf16 v[78:81], v[130:133], v[192:195], v[78:81]
	v_mfma_f32_16x16x32_bf16 v[74:77], v[138:141], v[192:195], v[74:77]
	v_mfma_f32_16x16x32_bf16 v[126:129], v[134:137], v[150:153], v[126:129]
	v_mfma_f32_16x16x32_bf16 v[122:125], v[142:145], v[150:153], v[122:125]
	v_mfma_f32_16x16x32_bf16 v[110:113], v[134:137], v[180:183], v[110:113]
	v_mfma_f32_16x16x32_bf16 v[106:109], v[142:145], v[180:183], v[106:109]
	v_mfma_f32_16x16x32_bf16 v[94:97], v[134:137], v[188:191], v[94:97]
	v_mfma_f32_16x16x32_bf16 v[90:93], v[142:145], v[188:191], v[90:93]
	v_mfma_f32_16x16x32_bf16 v[78:81], v[134:137], v[196:199], v[78:81]
	v_mfma_f32_16x16x32_bf16 v[74:77], v[142:145], v[196:199], v[74:77]
	s_barrier
	v_add_u32_e32 v0, 0x14000, v224
	s_add_i32 vcc_lo, s97, 0x10000
	s_mov_b32 m0, vcc_lo
	ds_read_b128 v[200:203], v0
	ds_read_b128 v[230:233], v0 offset:1024
	ds_read_b128 v[234:237], v0 offset:2048
	ds_read_b128 v[238:241], v0 offset:3072
	global_load_lds_dwordx4 v158, s[46:47]
	s_add_i32 m0, vcc_lo, 0x2000
	s_nop 0
	global_load_lds_dwordx4 v162, s[46:47]
	s_waitcnt vmcnt(6)
	s_barrier
	s_waitcnt lgkmcnt(0)
	v_mfma_f32_16x16x32_bf16 v[118:121], v[200:203], v[146:149], v[118:121]
	v_mfma_f32_16x16x32_bf16 v[114:117], v[234:237], v[146:149], v[114:117]
	v_mfma_f32_16x16x32_bf16 v[102:105], v[200:203], v[176:179], v[102:105]
	v_mfma_f32_16x16x32_bf16 v[98:101], v[234:237], v[176:179], v[98:101]
	v_mfma_f32_16x16x32_bf16 v[86:89], v[200:203], v[184:187], v[86:89]
	v_mfma_f32_16x16x32_bf16 v[82:85], v[234:237], v[184:187], v[82:85]
	v_mfma_f32_16x16x32_bf16 v[70:73], v[200:203], v[192:195], v[70:73]
	v_mfma_f32_16x16x32_bf16 v[66:69], v[234:237], v[192:195], v[66:69]
	v_mfma_f32_16x16x32_bf16 v[118:121], v[230:233], v[150:153], v[118:121]
	v_mfma_f32_16x16x32_bf16 v[114:117], v[238:241], v[150:153], v[114:117]
	v_mfma_f32_16x16x32_bf16 v[102:105], v[230:233], v[180:183], v[102:105]
	v_mfma_f32_16x16x32_bf16 v[98:101], v[238:241], v[180:183], v[98:101]
	v_mfma_f32_16x16x32_bf16 v[86:89], v[230:233], v[188:191], v[86:89]
	v_mfma_f32_16x16x32_bf16 v[82:85], v[238:241], v[188:191], v[82:85]
	v_mfma_f32_16x16x32_bf16 v[70:73], v[230:233], v[196:199], v[70:73]
	v_mfma_f32_16x16x32_bf16 v[66:69], v[238:241], v[196:199], v[66:69]
	s_barrier
	s_mov_b32 m0, s98
	ds_read_b128 v[146:149], v229 offset:16384
	ds_read_b128 v[150:153], v229 offset:17408
	ds_read_b128 v[176:179], v229 offset:18432
	ds_read_b128 v[180:183], v229 offset:19456
	ds_read_b128 v[184:187], v229 offset:20480
	ds_read_b128 v[188:191], v229 offset:21504
	ds_read_b128 v[192:195], v229 offset:22528
	ds_read_b128 v[196:199], v229 offset:23552
	global_load_lds_dwordx4 v156, s[44:45]
	s_mov_b32 m0, s99
	s_add_u32 s46, s46, s95
	global_load_lds_dwordx4 v160, s[44:45]
	s_addc_u32 s47, s47, 0
	s_barrier
	s_waitcnt lgkmcnt(0)
	v_mfma_f32_16x16x32_bf16 v[62:65], v[130:133], v[146:149], v[62:65]
	v_mfma_f32_16x16x32_bf16 v[58:61], v[138:141], v[146:149], v[58:61]
	v_mfma_f32_16x16x32_bf16 v[46:49], v[130:133], v[176:179], v[46:49]
	v_mfma_f32_16x16x32_bf16 v[42:45], v[138:141], v[176:179], v[42:45]
	v_mfma_f32_16x16x32_bf16 v[30:33], v[130:133], v[184:187], v[30:33]
	v_mfma_f32_16x16x32_bf16 v[26:29], v[138:141], v[184:187], v[26:29]
	v_mfma_f32_16x16x32_bf16 v[14:17], v[130:133], v[192:195], v[14:17]
	v_mfma_f32_16x16x32_bf16 v[10:13], v[138:141], v[192:195], v[10:13]
	v_mfma_f32_16x16x32_bf16 v[62:65], v[134:137], v[150:153], v[62:65]
	v_mfma_f32_16x16x32_bf16 v[58:61], v[142:145], v[150:153], v[58:61]
	v_mfma_f32_16x16x32_bf16 v[46:49], v[134:137], v[180:183], v[46:49]
	v_mfma_f32_16x16x32_bf16 v[42:45], v[142:145], v[180:183], v[42:45]
	v_mfma_f32_16x16x32_bf16 v[30:33], v[134:137], v[188:191], v[30:33]
	v_mfma_f32_16x16x32_bf16 v[26:29], v[142:145], v[188:191], v[26:29]
	v_mfma_f32_16x16x32_bf16 v[14:17], v[134:137], v[196:199], v[14:17]
	v_mfma_f32_16x16x32_bf16 v[10:13], v[142:145], v[196:199], v[10:13]
	s_barrier
	s_add_i32 vcc_lo, s97, 0x14000
	s_add_i32 vcc_hi, s97, 0x16000
	s_mov_b32 m0, vcc_lo
	s_add_u32 s44, s44, s20
	global_load_lds_dwordx4 v158, s[46:47]
	s_mov_b32 m0, vcc_hi
	s_addc_u32 s45, s45, 0
	global_load_lds_dwordx4 v162, s[46:47]
	v_add_u32_e32 v0, 0x18000, v224
	ds_read_b128 v[130:133], v0
	ds_read_b128 v[134:137], v0 offset:1024
	ds_read_b128 v[138:141], v0 offset:2048
	ds_read_b128 v[142:145], v0 offset:3072
	s_waitcnt vmcnt(6)
	s_barrier
	v_mfma_f32_16x16x32_bf16 v[54:57], v[200:203], v[146:149], v[54:57]
	v_mfma_f32_16x16x32_bf16 v[50:53], v[234:237], v[146:149], v[50:53]
	v_mfma_f32_16x16x32_bf16 v[38:41], v[200:203], v[176:179], v[38:41]
	v_mfma_f32_16x16x32_bf16 v[34:37], v[234:237], v[176:179], v[34:37]
	v_mfma_f32_16x16x32_bf16 v[22:25], v[200:203], v[184:187], v[22:25]
	v_mfma_f32_16x16x32_bf16 v[18:21], v[234:237], v[184:187], v[18:21]
	v_mfma_f32_16x16x32_bf16 v[6:9], v[200:203], v[192:195], v[6:9]
	v_mfma_f32_16x16x32_bf16 v[2:5], v[234:237], v[192:195], v[2:5]
	v_mfma_f32_16x16x32_bf16 v[54:57], v[230:233], v[150:153], v[54:57]
	v_mfma_f32_16x16x32_bf16 v[50:53], v[238:241], v[150:153], v[50:53]
	v_mfma_f32_16x16x32_bf16 v[38:41], v[230:233], v[180:183], v[38:41]
	v_mfma_f32_16x16x32_bf16 v[34:37], v[238:241], v[180:183], v[34:37]
	v_mfma_f32_16x16x32_bf16 v[22:25], v[230:233], v[188:191], v[22:25]
	v_mfma_f32_16x16x32_bf16 v[18:21], v[238:241], v[188:191], v[18:21]
	v_mfma_f32_16x16x32_bf16 v[6:9], v[230:233], v[196:199], v[6:9]
	v_mfma_f32_16x16x32_bf16 v[2:5], v[238:241], v[196:199], v[2:5]
	s_barrier
	s_mov_b32 m0, s94
	ds_read_b128 v[146:149], v229 offset:32768
	ds_read_b128 v[150:153], v229 offset:33792
	ds_read_b128 v[176:179], v229 offset:34816
	ds_read_b128 v[180:183], v229 offset:35840
	ds_read_b128 v[184:187], v229 offset:36864
	ds_read_b128 v[188:191], v229 offset:37888
	ds_read_b128 v[192:195], v229 offset:38912
	ds_read_b128 v[196:199], v229 offset:39936
	global_load_lds_dwordx4 v156, s[44:45]
	s_mov_b32 m0, s65
	s_nop 0
	global_load_lds_dwordx4 v160, s[44:45]
	s_waitcnt lgkmcnt(8)
	s_barrier
	s_waitcnt lgkmcnt(0)
	v_mfma_f32_16x16x32_bf16 v[126:129], v[130:133], v[146:149], v[126:129]
	v_mfma_f32_16x16x32_bf16 v[122:125], v[138:141], v[146:149], v[122:125]
	v_mfma_f32_16x16x32_bf16 v[110:113], v[130:133], v[176:179], v[110:113]
	v_mfma_f32_16x16x32_bf16 v[106:109], v[138:141], v[176:179], v[106:109]
	v_mfma_f32_16x16x32_bf16 v[94:97], v[130:133], v[184:187], v[94:97]
	v_mfma_f32_16x16x32_bf16 v[90:93], v[138:141], v[184:187], v[90:93]
	v_mfma_f32_16x16x32_bf16 v[78:81], v[130:133], v[192:195], v[78:81]
	v_mfma_f32_16x16x32_bf16 v[74:77], v[138:141], v[192:195], v[74:77]
	v_mfma_f32_16x16x32_bf16 v[126:129], v[134:137], v[150:153], v[126:129]
	v_mfma_f32_16x16x32_bf16 v[122:125], v[142:145], v[150:153], v[122:125]
	v_mfma_f32_16x16x32_bf16 v[110:113], v[134:137], v[180:183], v[110:113]
	v_mfma_f32_16x16x32_bf16 v[106:109], v[142:145], v[180:183], v[106:109]
	v_mfma_f32_16x16x32_bf16 v[94:97], v[134:137], v[188:191], v[94:97]
	v_mfma_f32_16x16x32_bf16 v[90:93], v[142:145], v[188:191], v[90:93]
	v_mfma_f32_16x16x32_bf16 v[78:81], v[134:137], v[196:199], v[78:81]
	v_mfma_f32_16x16x32_bf16 v[74:77], v[142:145], v[196:199], v[74:77]
	s_barrier
	s_sub_u32 s46, s46, s95
	s_subb_u32 s47, s47, 0
	v_add_u32_e32 v0, 0x1c000, v224
	s_add_i32 vcc_lo, s97, 0x17f80
	s_add_i32 vcc_hi, s97, 0x19f80
	s_mov_b32 m0, vcc_lo
	ds_read_b128 v[200:203], v0
	ds_read_b128 v[230:233], v0 offset:1024
	ds_read_b128 v[234:237], v0 offset:2048
	ds_read_b128 v[238:241], v0 offset:3072
	global_load_lds_dwordx4 v158, s[46:47] offset:128
	s_mov_b32 m0, vcc_hi
	s_sub_u32 s44, s44, s20
	global_load_lds_dwordx4 v162, s[46:47] offset:128
	s_subb_u32 s45, s45, 0
	s_waitcnt vmcnt(6)
	s_barrier
	s_waitcnt lgkmcnt(0)
	v_mfma_f32_16x16x32_bf16 v[118:121], v[200:203], v[146:149], v[118:121]
	v_mfma_f32_16x16x32_bf16 v[114:117], v[234:237], v[146:149], v[114:117]
	v_mfma_f32_16x16x32_bf16 v[102:105], v[200:203], v[176:179], v[102:105]
	v_mfma_f32_16x16x32_bf16 v[98:101], v[234:237], v[176:179], v[98:101]
	v_mfma_f32_16x16x32_bf16 v[86:89], v[200:203], v[184:187], v[86:89]
	v_mfma_f32_16x16x32_bf16 v[82:85], v[234:237], v[184:187], v[82:85]
	v_mfma_f32_16x16x32_bf16 v[70:73], v[200:203], v[192:195], v[70:73]
	v_mfma_f32_16x16x32_bf16 v[66:69], v[234:237], v[192:195], v[66:69]
	v_mfma_f32_16x16x32_bf16 v[118:121], v[230:233], v[150:153], v[118:121]
	v_mfma_f32_16x16x32_bf16 v[114:117], v[238:241], v[150:153], v[114:117]
	v_mfma_f32_16x16x32_bf16 v[102:105], v[230:233], v[180:183], v[102:105]
	v_mfma_f32_16x16x32_bf16 v[98:101], v[238:241], v[180:183], v[98:101]
	v_mfma_f32_16x16x32_bf16 v[86:89], v[230:233], v[188:191], v[86:89]
	v_mfma_f32_16x16x32_bf16 v[82:85], v[238:241], v[188:191], v[82:85]
	v_mfma_f32_16x16x32_bf16 v[70:73], v[230:233], v[196:199], v[70:73]
	v_mfma_f32_16x16x32_bf16 v[66:69], v[238:241], v[196:199], v[66:69]
	s_barrier
	s_add_i32 m0, s87, 0xffffff80
	ds_read_b128 v[146:149], v229 offset:49152
	ds_read_b128 v[150:153], v229 offset:50176
	ds_read_b128 v[176:179], v229 offset:51200
	ds_read_b128 v[180:183], v229 offset:52224
	ds_read_b128 v[184:187], v229 offset:53248
	ds_read_b128 v[188:191], v229 offset:54272
	ds_read_b128 v[192:195], v229 offset:55296
	ds_read_b128 v[196:199], v229 offset:56320
	global_load_lds_dwordx4 v156, s[44:45] offset:128
	s_add_i32 m0, s29, 0xffffff80
	s_add_u32 s46, s46, s95
	global_load_lds_dwordx4 v160, s[44:45] offset:128
	s_addc_u32 s47, s47, 0
	s_barrier
	s_waitcnt lgkmcnt(0)
	v_mfma_f32_16x16x32_bf16 v[62:65], v[130:133], v[146:149], v[62:65]
	v_mfma_f32_16x16x32_bf16 v[58:61], v[138:141], v[146:149], v[58:61]
	v_mfma_f32_16x16x32_bf16 v[46:49], v[130:133], v[176:179], v[46:49]
	v_mfma_f32_16x16x32_bf16 v[42:45], v[138:141], v[176:179], v[42:45]
	v_mfma_f32_16x16x32_bf16 v[30:33], v[130:133], v[184:187], v[30:33]
	v_mfma_f32_16x16x32_bf16 v[26:29], v[138:141], v[184:187], v[26:29]
	v_mfma_f32_16x16x32_bf16 v[14:17], v[130:133], v[192:195], v[14:17]
	v_mfma_f32_16x16x32_bf16 v[10:13], v[138:141], v[192:195], v[10:13]
	v_mfma_f32_16x16x32_bf16 v[62:65], v[134:137], v[150:153], v[62:65]
	v_mfma_f32_16x16x32_bf16 v[58:61], v[142:145], v[150:153], v[58:61]
	v_mfma_f32_16x16x32_bf16 v[46:49], v[134:137], v[180:183], v[46:49]
	v_mfma_f32_16x16x32_bf16 v[42:45], v[142:145], v[180:183], v[42:45]
	v_mfma_f32_16x16x32_bf16 v[30:33], v[134:137], v[188:191], v[30:33]
	v_mfma_f32_16x16x32_bf16 v[26:29], v[142:145], v[188:191], v[26:29]
	v_mfma_f32_16x16x32_bf16 v[14:17], v[134:137], v[196:199], v[14:17]
	v_mfma_f32_16x16x32_bf16 v[10:13], v[142:145], v[196:199], v[10:13]
	s_barrier
	s_add_i32 vcc_lo, s97, 0x1bf80
	s_add_i32 vcc_hi, s97, 0x1df80
	s_mov_b32 m0, vcc_lo
	s_add_u32 s0, s0, 0x100
	global_load_lds_dwordx4 v158, s[46:47] offset:128
	s_mov_b32 m0, vcc_hi
	s_addc_u32 s1, s1, 0
	global_load_lds_dwordx4 v162, s[46:47] offset:128
	v_add_u32_e32 v0, 0x10000, v224
	ds_read_b128 v[130:133], v0
	ds_read_b128 v[134:137], v0 offset:1024
	ds_read_b128 v[138:141], v0 offset:2048
	ds_read_b128 v[142:145], v0 offset:3072
	s_add_u32 s48, s48, 0x100
	s_addc_u32 s49, s49, 0
	s_cmp_ge_i32 s71, s6
	s_cselect_b64 vcc, -1, 0
	s_mov_b32 s44, s71
	s_add_i32 s71, s44, 2
	s_add_u32 s46, s0, 0x80
	s_addc_u32 s45, s1, 0
	s_cmp_eq_u32 s43, s44
	s_cselect_b32 s44, s72, s46
	s_cselect_b32 s45, s73, s45
	s_cselect_b32 s47, s75, s49
	s_cselect_b32 s46, s74, s48
	s_waitcnt vmcnt(6)
	s_barrier
	v_mfma_f32_16x16x32_bf16 v[54:57], v[200:203], v[146:149], v[54:57]
	v_mfma_f32_16x16x32_bf16 v[50:53], v[234:237], v[146:149], v[50:53]
	v_mfma_f32_16x16x32_bf16 v[38:41], v[200:203], v[176:179], v[38:41]
	v_mfma_f32_16x16x32_bf16 v[34:37], v[234:237], v[176:179], v[34:37]
	v_mfma_f32_16x16x32_bf16 v[22:25], v[200:203], v[184:187], v[22:25]
	v_mfma_f32_16x16x32_bf16 v[18:21], v[234:237], v[184:187], v[18:21]
	v_mfma_f32_16x16x32_bf16 v[6:9], v[200:203], v[192:195], v[6:9]
	v_mfma_f32_16x16x32_bf16 v[2:5], v[234:237], v[192:195], v[2:5]
	v_mfma_f32_16x16x32_bf16 v[54:57], v[230:233], v[150:153], v[54:57]
	v_mfma_f32_16x16x32_bf16 v[50:53], v[238:241], v[150:153], v[50:53]
	v_mfma_f32_16x16x32_bf16 v[38:41], v[230:233], v[180:183], v[38:41]
	v_mfma_f32_16x16x32_bf16 v[34:37], v[238:241], v[180:183], v[34:37]
	v_mfma_f32_16x16x32_bf16 v[22:25], v[230:233], v[188:191], v[22:25]
	v_mfma_f32_16x16x32_bf16 v[18:21], v[238:241], v[188:191], v[18:21]
	v_mfma_f32_16x16x32_bf16 v[6:9], v[230:233], v[196:199], v[6:9]
	v_mfma_f32_16x16x32_bf16 v[2:5], v[238:241], v[196:199], v[2:5]
	s_barrier
	s_cbranch_vccz .LBB0_386
	s_lshl_b32 s46, s77, 8
	s_cmp_lt_i32 s64, 1
	s_mov_b64 s[0:1], -1
	s_cbranch_scc1 .LBB0_403
